# final FF2 + final norm fused in registers: the last residual X is never written back, row sums of squares exchanged through 1 KB records, output stored from the accumulators
# speedup vs baseline: 1.0266x; 1.0130x over previous
.LBB0_2049:
	ds_read_b128 v[144:147], v155
	ds_read_b128 v[148:151], v155 offset:1024
	ds_read_b128 v[158:161], v155 offset:2048
	ds_read_b128 v[162:165], v155 offset:3072
	s_add_u32 s33, s40, 0x4000
	s_addc_u32 s48, s41, 0
	s_cmp_eq_u32 s80, 60
	s_cselect_b32 s52, s76, s33
	s_cselect_b32 s53, s31, s48
	s_cselect_b32 s48, s77, s78
	s_cselect_b32 s49, s29, s79
	s_add_u32 s50, s52, 0x8000
	s_addc_u32 s51, s53, 0
	v_lshl_add_u64 v[206:207], s[40:41], 0, v[138:139]
	s_add_i32 m0, s58, 0xc000
	ds_read_b128 v[166:169], v156
	ds_read_b128 v[178:181], v156 offset:1024
	ds_read_b128 v[182:185], v156 offset:2048
	ds_read_b128 v[186:189], v156 offset:3072
	ds_read_b128 v[190:193], v156 offset:4096
	ds_read_b128 v[194:197], v156 offset:5120
	ds_read_b128 v[198:201], v156 offset:6144
	ds_read_b128 v[202:205], v156 offset:7168
	global_load_lds_dwordx4 v[206:207], off
	v_lshl_add_u64 v[206:207], s[40:41], 0, v[136:137]
	s_add_i32 m0, s58, 0xe000
	s_nop 0
	global_load_lds_dwordx4 v[206:207], off
	s_waitcnt lgkmcnt(8)
	s_barrier
	s_waitcnt lgkmcnt(0)
	s_setprio 1
	s_waitcnt lgkmcnt(0)
	v_mfma_f32_16x16x32_bf16 v[124:127], v[144:147], v[166:169], v[124:127]
	v_mfma_f32_16x16x32_bf16 v[120:123], v[158:161], v[166:169], v[120:123]
	v_mfma_f32_16x16x32_bf16 v[108:111], v[144:147], v[182:185], v[108:111]
	v_mfma_f32_16x16x32_bf16 v[104:107], v[158:161], v[182:185], v[104:107]
	v_mfma_f32_16x16x32_bf16 v[92:95], v[144:147], v[190:193], v[92:95]
	v_mfma_f32_16x16x32_bf16 v[88:91], v[158:161], v[190:193], v[88:91]
	v_mfma_f32_16x16x32_bf16 v[76:79], v[144:147], v[198:201], v[76:79]
	v_mfma_f32_16x16x32_bf16 v[72:75], v[158:161], v[198:201], v[72:75]
	v_mfma_f32_16x16x32_bf16 v[124:127], v[148:151], v[178:181], v[124:127]
	v_mfma_f32_16x16x32_bf16 v[120:123], v[162:165], v[178:181], v[120:123]
	v_mfma_f32_16x16x32_bf16 v[108:111], v[148:151], v[186:189], v[108:111]
	v_mfma_f32_16x16x32_bf16 v[104:107], v[162:165], v[186:189], v[104:107]
	v_mfma_f32_16x16x32_bf16 v[92:95], v[148:151], v[194:197], v[92:95]
	v_mfma_f32_16x16x32_bf16 v[88:91], v[162:165], v[194:197], v[88:91]
	v_mfma_f32_16x16x32_bf16 v[76:79], v[148:151], v[202:205], v[76:79]
	v_mfma_f32_16x16x32_bf16 v[72:75], v[162:165], v[202:205], v[72:75]
	s_setprio 0
	s_barrier
	s_add_i32 s33, s68, s57
	v_lshl_add_u64 v[222:223], s[48:49], 0, v[132:133]
	s_mov_b32 m0, s33
	ds_read_b128 v[206:209], v157
	ds_read_b128 v[210:213], v157 offset:1024
	ds_read_b128 v[214:217], v157 offset:2048
	ds_read_b128 v[218:221], v157 offset:3072
	global_load_lds_dwordx4 v[222:223], off
	v_lshl_add_u64 v[224:225], s[48:49], 0, v[128:129]
	s_add_i32 m0, s33, 0x2000
	s_nop 0
	global_load_lds_dwordx4 v[224:225], off
	s_barrier
	s_waitcnt lgkmcnt(0)
	s_setprio 1
	s_waitcnt lgkmcnt(0)
	v_mfma_f32_16x16x32_bf16 v[116:119], v[206:209], v[166:169], v[116:119]
	v_mfma_f32_16x16x32_bf16 v[112:115], v[214:217], v[166:169], v[112:115]
	v_mfma_f32_16x16x32_bf16 v[100:103], v[206:209], v[182:185], v[100:103]
	v_mfma_f32_16x16x32_bf16 v[96:99], v[214:217], v[182:185], v[96:99]
	v_mfma_f32_16x16x32_bf16 v[84:87], v[206:209], v[190:193], v[84:87]
	v_mfma_f32_16x16x32_bf16 v[80:83], v[214:217], v[190:193], v[80:83]
	v_mfma_f32_16x16x32_bf16 v[68:71], v[206:209], v[198:201], v[68:71]
	v_mfma_f32_16x16x32_bf16 v[64:67], v[214:217], v[198:201], v[64:67]
	v_mfma_f32_16x16x32_bf16 v[116:119], v[210:213], v[178:181], v[116:119]
	v_mfma_f32_16x16x32_bf16 v[112:115], v[218:221], v[178:181], v[112:115]
	v_mfma_f32_16x16x32_bf16 v[100:103], v[210:213], v[186:189], v[100:103]
	v_mfma_f32_16x16x32_bf16 v[96:99], v[218:221], v[186:189], v[96:99]
	v_mfma_f32_16x16x32_bf16 v[84:87], v[210:213], v[194:197], v[84:87]
	v_mfma_f32_16x16x32_bf16 v[80:83], v[218:221], v[194:197], v[80:83]
	v_mfma_f32_16x16x32_bf16 v[68:71], v[210:213], v[202:205], v[68:71]
	v_mfma_f32_16x16x32_bf16 v[64:67], v[218:221], v[202:205], v[64:67]
	s_setprio 0
	s_mov_b32 m0, s58
	v_lshl_add_u64 v[226:227], s[52:53], 0, v[134:135]
	s_barrier
	ds_read_b128 v[166:169], v156 offset:16384
	ds_read_b128 v[178:181], v156 offset:17408
	ds_read_b128 v[182:185], v156 offset:18432
	ds_read_b128 v[186:189], v156 offset:19456
	ds_read_b128 v[190:193], v156 offset:20480
	ds_read_b128 v[194:197], v156 offset:21504
	ds_read_b128 v[198:201], v156 offset:22528
	ds_read_b128 v[202:205], v156 offset:23552
	global_load_lds_dwordx4 v[226:227], off
	v_lshl_add_u64 v[226:227], s[52:53], 0, v[130:131]
	s_mov_b32 m0, s59
	s_nop 0
	global_load_lds_dwordx4 v[226:227], off
	s_barrier
	s_waitcnt lgkmcnt(0)
	s_setprio 1
	s_waitcnt lgkmcnt(0)
	v_mfma_f32_16x16x32_bf16 v[60:63], v[144:147], v[166:169], v[60:63]
	v_mfma_f32_16x16x32_bf16 v[56:59], v[158:161], v[166:169], v[56:59]
	v_mfma_f32_16x16x32_bf16 v[44:47], v[144:147], v[182:185], v[44:47]
	v_mfma_f32_16x16x32_bf16 v[40:43], v[158:161], v[182:185], v[40:43]
	v_mfma_f32_16x16x32_bf16 v[28:31], v[144:147], v[190:193], v[28:31]
	v_mfma_f32_16x16x32_bf16 v[24:27], v[158:161], v[190:193], v[24:27]
	v_mfma_f32_16x16x32_bf16 v[12:15], v[144:147], v[198:201], v[12:15]
	v_mfma_f32_16x16x32_bf16 v[8:11], v[158:161], v[198:201], v[8:11]
	v_mfma_f32_16x16x32_bf16 v[60:63], v[148:151], v[178:181], v[60:63]
	v_mfma_f32_16x16x32_bf16 v[56:59], v[162:165], v[178:181], v[56:59]
	v_mfma_f32_16x16x32_bf16 v[44:47], v[148:151], v[186:189], v[44:47]
	v_mfma_f32_16x16x32_bf16 v[40:43], v[162:165], v[186:189], v[40:43]
	v_mfma_f32_16x16x32_bf16 v[28:31], v[148:151], v[194:197], v[28:31]
	v_mfma_f32_16x16x32_bf16 v[24:27], v[162:165], v[194:197], v[24:27]
	v_mfma_f32_16x16x32_bf16 v[12:15], v[148:151], v[202:205], v[12:15]
	v_mfma_f32_16x16x32_bf16 v[8:11], v[162:165], v[202:205], v[8:11]
	s_setprio 0
	s_barrier
	s_add_u32 s82, s48, 0x100000
	s_addc_u32 s83, s49, 0
	s_add_i32 s33, s69, s57
	v_lshl_add_u64 v[144:145], s[82:83], 0, v[132:133]
	s_mov_b32 m0, s33
	s_nop 0
	global_load_lds_dwordx4 v[144:145], off
	v_lshl_add_u64 v[144:145], s[82:83], 0, v[128:129]
	s_add_i32 m0, s33, 0x2000
	s_nop 0
	global_load_lds_dwordx4 v[144:145], off
	s_waitcnt vmcnt(6)
	s_barrier
	s_setprio 1
	v_mfma_f32_16x16x32_bf16 v[52:55], v[206:209], v[166:169], v[52:55]
	v_mfma_f32_16x16x32_bf16 v[48:51], v[214:217], v[166:169], v[48:51]
	v_mfma_f32_16x16x32_bf16 v[36:39], v[206:209], v[182:185], v[36:39]
	v_mfma_f32_16x16x32_bf16 v[32:35], v[214:217], v[182:185], v[32:35]
	v_mfma_f32_16x16x32_bf16 v[20:23], v[206:209], v[190:193], v[20:23]
	v_mfma_f32_16x16x32_bf16 v[16:19], v[214:217], v[190:193], v[16:19]
	v_mfma_f32_16x16x32_bf16 v[4:7], v[206:209], v[198:201], v[4:7]
	v_mfma_f32_16x16x32_bf16 v[0:3], v[214:217], v[198:201], v[0:3]
	v_mfma_f32_16x16x32_bf16 v[52:55], v[210:213], v[178:181], v[52:55]
	v_mfma_f32_16x16x32_bf16 v[48:51], v[218:221], v[178:181], v[48:51]
	v_mfma_f32_16x16x32_bf16 v[36:39], v[210:213], v[186:189], v[36:39]
	v_mfma_f32_16x16x32_bf16 v[32:35], v[218:221], v[186:189], v[32:35]
	v_mfma_f32_16x16x32_bf16 v[20:23], v[210:213], v[194:197], v[20:23]
	v_mfma_f32_16x16x32_bf16 v[16:19], v[218:221], v[194:197], v[16:19]
	v_mfma_f32_16x16x32_bf16 v[4:7], v[210:213], v[202:205], v[4:7]
	v_mfma_f32_16x16x32_bf16 v[0:3], v[218:221], v[202:205], v[0:3]
	s_setprio 0
	s_add_i32 s33, 0, 0x18000
	v_add_u32_e32 v162, s33, v153
	s_barrier
	ds_read_b128 v[144:147], v162
	ds_read_b128 v[148:151], v162 offset:1024
	ds_read_b128 v[158:161], v162 offset:2048
	ds_read_b128 v[162:165], v162 offset:3072
	s_add_u32 s52, s52, 0x4000
	s_addc_u32 s53, s53, 0
	s_mov_b32 m0, s60
	v_lshl_add_u64 v[206:207], s[52:53], 0, v[134:135]
	ds_read_b128 v[166:169], v156 offset:32768
	ds_read_b128 v[178:181], v156 offset:33792
	ds_read_b128 v[182:185], v156 offset:34816
	ds_read_b128 v[186:189], v156 offset:35840
	ds_read_b128 v[190:193], v156 offset:36864
	ds_read_b128 v[194:197], v156 offset:37888
	ds_read_b128 v[198:201], v156 offset:38912
	ds_read_b128 v[202:205], v156 offset:39936
	global_load_lds_dwordx4 v[206:207], off
	v_lshl_add_u64 v[206:207], s[52:53], 0, v[130:131]
	s_mov_b32 m0, s61
	s_nop 0
	global_load_lds_dwordx4 v[206:207], off
	s_waitcnt lgkmcnt(8)
	s_barrier
	s_waitcnt lgkmcnt(0)
	s_setprio 1
	s_waitcnt lgkmcnt(0)
	v_mfma_f32_16x16x32_bf16 v[124:127], v[144:147], v[166:169], v[124:127]
	v_mfma_f32_16x16x32_bf16 v[120:123], v[158:161], v[166:169], v[120:123]
	v_mfma_f32_16x16x32_bf16 v[108:111], v[144:147], v[182:185], v[108:111]
	v_mfma_f32_16x16x32_bf16 v[104:107], v[158:161], v[182:185], v[104:107]
	v_mfma_f32_16x16x32_bf16 v[92:95], v[144:147], v[190:193], v[92:95]
	v_mfma_f32_16x16x32_bf16 v[88:91], v[158:161], v[190:193], v[88:91]
	v_mfma_f32_16x16x32_bf16 v[76:79], v[144:147], v[198:201], v[76:79]
	v_mfma_f32_16x16x32_bf16 v[72:75], v[158:161], v[198:201], v[72:75]
	v_mfma_f32_16x16x32_bf16 v[124:127], v[148:151], v[178:181], v[124:127]
	v_mfma_f32_16x16x32_bf16 v[120:123], v[162:165], v[178:181], v[120:123]
	v_mfma_f32_16x16x32_bf16 v[108:111], v[148:151], v[186:189], v[108:111]
	v_mfma_f32_16x16x32_bf16 v[104:107], v[162:165], v[186:189], v[104:107]
	v_mfma_f32_16x16x32_bf16 v[92:95], v[148:151], v[194:197], v[92:95]
	v_mfma_f32_16x16x32_bf16 v[88:91], v[162:165], v[194:197], v[88:91]
	v_mfma_f32_16x16x32_bf16 v[76:79], v[148:151], v[202:205], v[76:79]
	v_mfma_f32_16x16x32_bf16 v[72:75], v[162:165], v[202:205], v[72:75]
	s_setprio 0
	s_barrier
	s_add_i32 s52, 0, 0x1c000
	s_add_i32 s33, s33, s57
	v_add_u32_e32 v177, s52, v153
	v_lshl_add_u64 v[222:223], v[222:223], 0, s[18:19]
	s_mov_b32 m0, s33
	ds_read_b128 v[206:209], v177
	ds_read_b128 v[210:213], v177 offset:1024
	ds_read_b128 v[214:217], v177 offset:2048
	ds_read_b128 v[218:221], v177 offset:3072
	global_load_lds_dwordx4 v[222:223], off
	v_lshl_add_u64 v[222:223], v[224:225], 0, s[18:19]
	s_add_i32 m0, s33, 0x2000
	s_nop 0
	global_load_lds_dwordx4 v[222:223], off
	s_barrier
	s_waitcnt lgkmcnt(0)
	s_setprio 1
	s_waitcnt lgkmcnt(0)
	v_mfma_f32_16x16x32_bf16 v[116:119], v[206:209], v[166:169], v[116:119]
	v_mfma_f32_16x16x32_bf16 v[112:115], v[214:217], v[166:169], v[112:115]
	v_mfma_f32_16x16x32_bf16 v[100:103], v[206:209], v[182:185], v[100:103]
	v_mfma_f32_16x16x32_bf16 v[96:99], v[214:217], v[182:185], v[96:99]
	v_mfma_f32_16x16x32_bf16 v[84:87], v[206:209], v[190:193], v[84:87]
	v_mfma_f32_16x16x32_bf16 v[80:83], v[214:217], v[190:193], v[80:83]
	v_mfma_f32_16x16x32_bf16 v[68:71], v[206:209], v[198:201], v[68:71]
	v_mfma_f32_16x16x32_bf16 v[64:67], v[214:217], v[198:201], v[64:67]
	v_mfma_f32_16x16x32_bf16 v[116:119], v[210:213], v[178:181], v[116:119]
	v_mfma_f32_16x16x32_bf16 v[112:115], v[218:221], v[178:181], v[112:115]
	v_mfma_f32_16x16x32_bf16 v[100:103], v[210:213], v[186:189], v[100:103]
	v_mfma_f32_16x16x32_bf16 v[96:99], v[218:221], v[186:189], v[96:99]
	v_mfma_f32_16x16x32_bf16 v[84:87], v[210:213], v[194:197], v[84:87]
	v_mfma_f32_16x16x32_bf16 v[80:83], v[218:221], v[194:197], v[80:83]
	v_mfma_f32_16x16x32_bf16 v[68:71], v[210:213], v[202:205], v[68:71]
	v_mfma_f32_16x16x32_bf16 v[64:67], v[218:221], v[202:205], v[64:67]
	s_setprio 0
	s_mov_b32 m0, s62
	v_lshl_add_u64 v[222:223], s[50:51], 0, v[134:135]
	s_barrier
	ds_read_b128 v[166:169], v156 offset:49152
	ds_read_b128 v[178:181], v156 offset:50176
	ds_read_b128 v[182:185], v156 offset:51200
	ds_read_b128 v[186:189], v156 offset:52224
	ds_read_b128 v[190:193], v156 offset:53248
	ds_read_b128 v[194:197], v156 offset:54272
	ds_read_b128 v[198:201], v156 offset:55296
	ds_read_b128 v[202:205], v156 offset:56320
	global_load_lds_dwordx4 v[222:223], off
	v_lshl_add_u64 v[222:223], s[50:51], 0, v[130:131]
	s_mov_b32 m0, s63
	s_nop 0
	global_load_lds_dwordx4 v[222:223], off
	s_barrier
	s_waitcnt lgkmcnt(0)
	s_setprio 1
	s_waitcnt lgkmcnt(0)
	v_mfma_f32_16x16x32_bf16 v[60:63], v[144:147], v[166:169], v[60:63]
	v_mfma_f32_16x16x32_bf16 v[56:59], v[158:161], v[166:169], v[56:59]
	v_mfma_f32_16x16x32_bf16 v[44:47], v[144:147], v[182:185], v[44:47]
	v_mfma_f32_16x16x32_bf16 v[40:43], v[158:161], v[182:185], v[40:43]
	v_mfma_f32_16x16x32_bf16 v[28:31], v[144:147], v[190:193], v[28:31]
	v_mfma_f32_16x16x32_bf16 v[24:27], v[158:161], v[190:193], v[24:27]
	v_mfma_f32_16x16x32_bf16 v[12:15], v[144:147], v[198:201], v[12:15]
	v_mfma_f32_16x16x32_bf16 v[8:11], v[158:161], v[198:201], v[8:11]
	v_mfma_f32_16x16x32_bf16 v[60:63], v[148:151], v[178:181], v[60:63]
	v_mfma_f32_16x16x32_bf16 v[56:59], v[162:165], v[178:181], v[56:59]
	v_mfma_f32_16x16x32_bf16 v[44:47], v[148:151], v[186:189], v[44:47]
	v_mfma_f32_16x16x32_bf16 v[40:43], v[162:165], v[186:189], v[40:43]
	v_mfma_f32_16x16x32_bf16 v[28:31], v[148:151], v[194:197], v[28:31]
	v_mfma_f32_16x16x32_bf16 v[24:27], v[162:165], v[194:197], v[24:27]
	v_mfma_f32_16x16x32_bf16 v[12:15], v[148:151], v[202:205], v[12:15]
	v_mfma_f32_16x16x32_bf16 v[8:11], v[162:165], v[202:205], v[8:11]
	s_setprio 0
	s_barrier
	s_add_u32 s48, s48, 0x100080
	s_addc_u32 s49, s49, 0
	s_add_i32 s33, s52, s57
	v_lshl_add_u64 v[144:145], s[48:49], 0, v[132:133]
	s_mov_b32 m0, s33
	s_nop 0
	global_load_lds_dwordx4 v[144:145], off
	v_lshl_add_u64 v[144:145], s[48:49], 0, v[128:129]
	s_add_i32 m0, s33, 0x2000
	s_nop 0
	global_load_lds_dwordx4 v[144:145], off
	s_waitcnt vmcnt(6)
	s_barrier
	s_setprio 1
	v_mfma_f32_16x16x32_bf16 v[52:55], v[206:209], v[166:169], v[52:55]
	v_mfma_f32_16x16x32_bf16 v[48:51], v[214:217], v[166:169], v[48:51]
	v_mfma_f32_16x16x32_bf16 v[36:39], v[206:209], v[182:185], v[36:39]
	v_mfma_f32_16x16x32_bf16 v[32:35], v[214:217], v[182:185], v[32:35]
	v_mfma_f32_16x16x32_bf16 v[20:23], v[206:209], v[190:193], v[20:23]
	v_mfma_f32_16x16x32_bf16 v[16:19], v[214:217], v[190:193], v[16:19]
	v_mfma_f32_16x16x32_bf16 v[4:7], v[206:209], v[198:201], v[4:7]
	v_mfma_f32_16x16x32_bf16 v[0:3], v[214:217], v[198:201], v[0:3]
	v_mfma_f32_16x16x32_bf16 v[52:55], v[210:213], v[178:181], v[52:55]
	v_mfma_f32_16x16x32_bf16 v[48:51], v[218:221], v[178:181], v[48:51]
	v_mfma_f32_16x16x32_bf16 v[36:39], v[210:213], v[186:189], v[36:39]
	v_mfma_f32_16x16x32_bf16 v[32:35], v[218:221], v[186:189], v[32:35]
	v_mfma_f32_16x16x32_bf16 v[20:23], v[210:213], v[194:197], v[20:23]
	v_mfma_f32_16x16x32_bf16 v[16:19], v[218:221], v[194:197], v[16:19]
	v_mfma_f32_16x16x32_bf16 v[4:7], v[210:213], v[202:205], v[4:7]
	v_mfma_f32_16x16x32_bf16 v[0:3], v[218:221], v[202:205], v[0:3]
	s_setprio 0
	s_add_i32 s80, s80, 2
	s_add_u32 s78, s78, 0x100
	s_addc_u32 s79, s79, 0
	s_add_u32 s40, s40, 0x10000
	s_addc_u32 s41, s41, 0
	s_cmp_gt_u32 s80, 61
	s_barrier
	s_cbranch_scc0 .LBB0_2049
	s_lshl_b32 s82, s10, 8
	v_lshl_or_b32 v145, s75, 8, v154
	v_add_u32_e32 v144, s82, v152
	v_lshlrev_b32_e32 v145, 2, v145
	s_sub_u32 s83, s82, 0x1000
	s_lshr_b32 s83, s83, 11
	s_mul_i32 s83, s83, 6
	s_add_i32 s83, s83, 41
	s_cmp_gt_i32 s10, 15
	s_cselect_b32 s83, s83, 35
	s_lshl_b32 s83, s83, 12
	s_add_u32 s50, s66, s83
	s_addc_u32 s51, s67, 0
	v_lshl_add_u32 v146, v144, 12, v145
	global_load_dwordx4 v[148:151], v145, s[50:51]
	global_load_dwordx4 v[158:161], v145, s[50:51] offset:64
	global_load_dwordx4 v[162:165], v145, s[50:51] offset:512
	global_load_dwordx4 v[166:169], v145, s[50:51] offset:576
	s_mov_b64 s[84:85], s[12:13]
	s_mov_b64 s[86:87], s[12:13]
	v_mov_b32_e32 v226, 0
	v_mov_b32_e32 v227, 0
	v_mov_b32_e32 v228, 0
	v_mov_b32_e32 v229, 0
	v_mov_b32_e32 v230, 0
	v_mov_b32_e32 v231, 0
	v_mov_b32_e32 v232, 0
	v_mov_b32_e32 v233, 0
	global_load_dwordx4 v[178:181], v146, s[84:85]
	global_load_dwordx4 v[182:185], v146, s[84:85] offset:64
	global_load_dwordx4 v[186:189], v146, s[84:85] offset:512
	global_load_dwordx4 v[190:193], v146, s[84:85] offset:576
	s_add_u32 s84, s84, 0x10000
	s_addc_u32 s85, s85, 0
	global_load_dwordx4 v[194:197], v146, s[84:85]
	global_load_dwordx4 v[198:201], v146, s[84:85] offset:64
	global_load_dwordx4 v[202:205], v146, s[84:85] offset:512
	global_load_dwordx4 v[206:209], v146, s[84:85] offset:576
	s_add_u32 s84, s84, 0x10000
	s_addc_u32 s85, s85, 0
	global_load_dwordx4 v[210:213], v146, s[84:85]
	global_load_dwordx4 v[214:217], v146, s[84:85] offset:64
	global_load_dwordx4 v[218:221], v146, s[84:85] offset:512
	global_load_dwordx4 v[222:225], v146, s[84:85] offset:576
	s_waitcnt vmcnt(11)
	v_pk_fma_f32 v[124:125], v[124:125], v[148:149], v[178:179]
	v_pk_fma_f32 v[126:127], v[126:127], v[150:151], v[180:181]
	v_fmac_f32_e32 v226, v124, v124
	v_fmac_f32_e32 v226, v125, v125
	v_fmac_f32_e32 v226, v126, v126
	v_fmac_f32_e32 v226, v127, v127
	s_add_u32 s84, s84, 0x10000
	s_addc_u32 s85, s85, 0
	global_load_dwordx4 v[178:181], v146, s[84:85]
	s_waitcnt vmcnt(11)
	v_pk_fma_f32 v[120:121], v[120:121], v[158:159], v[182:183]
	v_pk_fma_f32 v[122:123], v[122:123], v[160:161], v[184:185]
	v_fmac_f32_e32 v226, v120, v120
	v_fmac_f32_e32 v226, v121, v121
	v_fmac_f32_e32 v226, v122, v122
	v_fmac_f32_e32 v226, v123, v123
	global_load_dwordx4 v[182:185], v146, s[84:85] offset:64
	s_waitcnt vmcnt(11)
	v_pk_fma_f32 v[116:117], v[116:117], v[162:163], v[186:187]
	v_pk_fma_f32 v[118:119], v[118:119], v[164:165], v[188:189]
	v_fmac_f32_e32 v226, v116, v116
	v_fmac_f32_e32 v226, v117, v117
	v_fmac_f32_e32 v226, v118, v118
	v_fmac_f32_e32 v226, v119, v119
	global_load_dwordx4 v[186:189], v146, s[84:85] offset:512
	s_waitcnt vmcnt(11)
	v_pk_fma_f32 v[112:113], v[112:113], v[166:167], v[190:191]
	v_pk_fma_f32 v[114:115], v[114:115], v[168:169], v[192:193]
	v_fmac_f32_e32 v226, v112, v112
	v_fmac_f32_e32 v226, v113, v113
	v_fmac_f32_e32 v226, v114, v114
	v_fmac_f32_e32 v226, v115, v115
	global_load_dwordx4 v[190:193], v146, s[84:85] offset:576
	s_waitcnt vmcnt(11)
	v_pk_fma_f32 v[108:109], v[108:109], v[148:149], v[194:195]
	v_pk_fma_f32 v[110:111], v[110:111], v[150:151], v[196:197]
	v_fmac_f32_e32 v227, v108, v108
	v_fmac_f32_e32 v227, v109, v109
	v_fmac_f32_e32 v227, v110, v110
	v_fmac_f32_e32 v227, v111, v111
	s_add_u32 s84, s84, 0x50000
	s_addc_u32 s85, s85, 0
	global_load_dwordx4 v[194:197], v146, s[84:85]
	s_waitcnt vmcnt(11)
	v_pk_fma_f32 v[104:105], v[104:105], v[158:159], v[198:199]
	v_pk_fma_f32 v[106:107], v[106:107], v[160:161], v[200:201]
	v_fmac_f32_e32 v227, v104, v104
	v_fmac_f32_e32 v227, v105, v105
	v_fmac_f32_e32 v227, v106, v106
	v_fmac_f32_e32 v227, v107, v107
	global_load_dwordx4 v[198:201], v146, s[84:85] offset:64
	s_waitcnt vmcnt(11)
	v_pk_fma_f32 v[100:101], v[100:101], v[162:163], v[202:203]
	v_pk_fma_f32 v[102:103], v[102:103], v[164:165], v[204:205]
	v_fmac_f32_e32 v227, v100, v100
	v_fmac_f32_e32 v227, v101, v101
	v_fmac_f32_e32 v227, v102, v102
	v_fmac_f32_e32 v227, v103, v103
	global_load_dwordx4 v[202:205], v146, s[84:85] offset:512
	s_waitcnt vmcnt(11)
	v_pk_fma_f32 v[96:97], v[96:97], v[166:167], v[206:207]
	v_pk_fma_f32 v[98:99], v[98:99], v[168:169], v[208:209]
	v_fmac_f32_e32 v227, v96, v96
	v_fmac_f32_e32 v227, v97, v97
	v_fmac_f32_e32 v227, v98, v98
	v_fmac_f32_e32 v227, v99, v99
	global_load_dwordx4 v[206:209], v146, s[84:85] offset:576
	s_waitcnt vmcnt(11)
	v_pk_fma_f32 v[92:93], v[92:93], v[148:149], v[210:211]
	v_pk_fma_f32 v[94:95], v[94:95], v[150:151], v[212:213]
	v_fmac_f32_e32 v228, v92, v92
	v_fmac_f32_e32 v228, v93, v93
	v_fmac_f32_e32 v228, v94, v94
	v_fmac_f32_e32 v228, v95, v95
	s_add_u32 s84, s84, 0x10000
	s_addc_u32 s85, s85, 0
	global_load_dwordx4 v[210:213], v146, s[84:85]
	s_waitcnt vmcnt(11)
	v_pk_fma_f32 v[88:89], v[88:89], v[158:159], v[214:215]
	v_pk_fma_f32 v[90:91], v[90:91], v[160:161], v[216:217]
	v_fmac_f32_e32 v228, v88, v88
	v_fmac_f32_e32 v228, v89, v89
	v_fmac_f32_e32 v228, v90, v90
	v_fmac_f32_e32 v228, v91, v91
	global_load_dwordx4 v[214:217], v146, s[84:85] offset:64
	s_waitcnt vmcnt(11)
	v_pk_fma_f32 v[84:85], v[84:85], v[162:163], v[218:219]
	v_pk_fma_f32 v[86:87], v[86:87], v[164:165], v[220:221]
	v_fmac_f32_e32 v228, v84, v84
	v_fmac_f32_e32 v228, v85, v85
	v_fmac_f32_e32 v228, v86, v86
	v_fmac_f32_e32 v228, v87, v87
	global_load_dwordx4 v[218:221], v146, s[84:85] offset:512
	s_waitcnt vmcnt(11)
	v_pk_fma_f32 v[80:81], v[80:81], v[166:167], v[222:223]
	v_pk_fma_f32 v[82:83], v[82:83], v[168:169], v[224:225]
	v_fmac_f32_e32 v228, v80, v80
	v_fmac_f32_e32 v228, v81, v81
	v_fmac_f32_e32 v228, v82, v82
	v_fmac_f32_e32 v228, v83, v83
	global_load_dwordx4 v[222:225], v146, s[84:85] offset:576
	s_waitcnt vmcnt(11)
	v_pk_fma_f32 v[76:77], v[76:77], v[148:149], v[178:179]
	v_pk_fma_f32 v[78:79], v[78:79], v[150:151], v[180:181]
	v_fmac_f32_e32 v229, v76, v76
	v_fmac_f32_e32 v229, v77, v77
	v_fmac_f32_e32 v229, v78, v78
	v_fmac_f32_e32 v229, v79, v79
	s_add_u32 s84, s84, 0x10000
	s_addc_u32 s85, s85, 0
	global_load_dwordx4 v[178:181], v146, s[84:85]
	s_waitcnt vmcnt(11)
	v_pk_fma_f32 v[72:73], v[72:73], v[158:159], v[182:183]
	v_pk_fma_f32 v[74:75], v[74:75], v[160:161], v[184:185]
	v_fmac_f32_e32 v229, v72, v72
	v_fmac_f32_e32 v229, v73, v73
	v_fmac_f32_e32 v229, v74, v74
	v_fmac_f32_e32 v229, v75, v75
	global_load_dwordx4 v[182:185], v146, s[84:85] offset:64
	s_waitcnt vmcnt(11)
	v_pk_fma_f32 v[68:69], v[68:69], v[162:163], v[186:187]
	v_pk_fma_f32 v[70:71], v[70:71], v[164:165], v[188:189]
	v_fmac_f32_e32 v229, v68, v68
	v_fmac_f32_e32 v229, v69, v69
	v_fmac_f32_e32 v229, v70, v70
	v_fmac_f32_e32 v229, v71, v71
	global_load_dwordx4 v[186:189], v146, s[84:85] offset:512
	s_waitcnt vmcnt(11)
	v_pk_fma_f32 v[64:65], v[64:65], v[166:167], v[190:191]
	v_pk_fma_f32 v[66:67], v[66:67], v[168:169], v[192:193]
	v_fmac_f32_e32 v229, v64, v64
	v_fmac_f32_e32 v229, v65, v65
	v_fmac_f32_e32 v229, v66, v66
	v_fmac_f32_e32 v229, v67, v67
	global_load_dwordx4 v[190:193], v146, s[84:85] offset:576
	s_waitcnt vmcnt(11)
	v_pk_fma_f32 v[60:61], v[60:61], v[148:149], v[194:195]
	v_pk_fma_f32 v[62:63], v[62:63], v[150:151], v[196:197]
	v_fmac_f32_e32 v230, v60, v60
	v_fmac_f32_e32 v230, v61, v61
	v_fmac_f32_e32 v230, v62, v62
	v_fmac_f32_e32 v230, v63, v63
	s_add_u32 s84, s84, 0x10000
	s_addc_u32 s85, s85, 0
	global_load_dwordx4 v[194:197], v146, s[84:85]
	s_waitcnt vmcnt(11)
	v_pk_fma_f32 v[56:57], v[56:57], v[158:159], v[198:199]
	v_pk_fma_f32 v[58:59], v[58:59], v[160:161], v[200:201]
	v_fmac_f32_e32 v230, v56, v56
	v_fmac_f32_e32 v230, v57, v57
	v_fmac_f32_e32 v230, v58, v58
	v_fmac_f32_e32 v230, v59, v59
	global_load_dwordx4 v[198:201], v146, s[84:85] offset:64
	s_waitcnt vmcnt(11)
	v_pk_fma_f32 v[52:53], v[52:53], v[162:163], v[202:203]
	v_pk_fma_f32 v[54:55], v[54:55], v[164:165], v[204:205]
	v_fmac_f32_e32 v230, v52, v52
	v_fmac_f32_e32 v230, v53, v53
	v_fmac_f32_e32 v230, v54, v54
	v_fmac_f32_e32 v230, v55, v55
	global_load_dwordx4 v[202:205], v146, s[84:85] offset:512
	s_waitcnt vmcnt(11)
	v_pk_fma_f32 v[48:49], v[48:49], v[166:167], v[206:207]
	v_pk_fma_f32 v[50:51], v[50:51], v[168:169], v[208:209]
	v_fmac_f32_e32 v230, v48, v48
	v_fmac_f32_e32 v230, v49, v49
	v_fmac_f32_e32 v230, v50, v50
	v_fmac_f32_e32 v230, v51, v51
	global_load_dwordx4 v[206:209], v146, s[84:85] offset:576
	s_waitcnt vmcnt(11)
	v_pk_fma_f32 v[44:45], v[44:45], v[148:149], v[210:211]
	v_pk_fma_f32 v[46:47], v[46:47], v[150:151], v[212:213]
	v_fmac_f32_e32 v231, v44, v44
	v_fmac_f32_e32 v231, v45, v45
	v_fmac_f32_e32 v231, v46, v46
	v_fmac_f32_e32 v231, v47, v47
	s_waitcnt vmcnt(10)
	v_pk_fma_f32 v[40:41], v[40:41], v[158:159], v[214:215]
	v_pk_fma_f32 v[42:43], v[42:43], v[160:161], v[216:217]
	v_fmac_f32_e32 v231, v40, v40
	v_fmac_f32_e32 v231, v41, v41
	v_fmac_f32_e32 v231, v42, v42
	v_fmac_f32_e32 v231, v43, v43
	s_waitcnt vmcnt(9)
	v_pk_fma_f32 v[36:37], v[36:37], v[162:163], v[218:219]
	v_pk_fma_f32 v[38:39], v[38:39], v[164:165], v[220:221]
	v_fmac_f32_e32 v231, v36, v36
	v_fmac_f32_e32 v231, v37, v37
	v_fmac_f32_e32 v231, v38, v38
	v_fmac_f32_e32 v231, v39, v39
	s_waitcnt vmcnt(8)
	v_pk_fma_f32 v[32:33], v[32:33], v[166:167], v[222:223]
	v_pk_fma_f32 v[34:35], v[34:35], v[168:169], v[224:225]
	v_fmac_f32_e32 v231, v32, v32
	v_fmac_f32_e32 v231, v33, v33
	v_fmac_f32_e32 v231, v34, v34
	v_fmac_f32_e32 v231, v35, v35
	s_waitcnt vmcnt(7)
	v_pk_fma_f32 v[28:29], v[28:29], v[148:149], v[178:179]
	v_pk_fma_f32 v[30:31], v[30:31], v[150:151], v[180:181]
	v_fmac_f32_e32 v232, v28, v28
	v_fmac_f32_e32 v232, v29, v29
	v_fmac_f32_e32 v232, v30, v30
	v_fmac_f32_e32 v232, v31, v31
	s_waitcnt vmcnt(6)
	v_pk_fma_f32 v[24:25], v[24:25], v[158:159], v[182:183]
	v_pk_fma_f32 v[26:27], v[26:27], v[160:161], v[184:185]
	v_fmac_f32_e32 v232, v24, v24
	v_fmac_f32_e32 v232, v25, v25
	v_fmac_f32_e32 v232, v26, v26
	v_fmac_f32_e32 v232, v27, v27
	s_waitcnt vmcnt(5)
	v_pk_fma_f32 v[20:21], v[20:21], v[162:163], v[186:187]
	v_pk_fma_f32 v[22:23], v[22:23], v[164:165], v[188:189]
	v_fmac_f32_e32 v232, v20, v20
	v_fmac_f32_e32 v232, v21, v21
	v_fmac_f32_e32 v232, v22, v22
	v_fmac_f32_e32 v232, v23, v23
	s_waitcnt vmcnt(4)
	v_pk_fma_f32 v[16:17], v[16:17], v[166:167], v[190:191]
	v_pk_fma_f32 v[18:19], v[18:19], v[168:169], v[192:193]
	v_fmac_f32_e32 v232, v16, v16
	v_fmac_f32_e32 v232, v17, v17
	v_fmac_f32_e32 v232, v18, v18
	v_fmac_f32_e32 v232, v19, v19
	s_waitcnt vmcnt(3)
	v_pk_fma_f32 v[12:13], v[12:13], v[148:149], v[194:195]
	v_pk_fma_f32 v[14:15], v[14:15], v[150:151], v[196:197]
	v_fmac_f32_e32 v233, v12, v12
	v_fmac_f32_e32 v233, v13, v13
	v_fmac_f32_e32 v233, v14, v14
	v_fmac_f32_e32 v233, v15, v15
	s_waitcnt vmcnt(2)
	v_pk_fma_f32 v[8:9], v[8:9], v[158:159], v[198:199]
	v_pk_fma_f32 v[10:11], v[10:11], v[160:161], v[200:201]
	v_fmac_f32_e32 v233, v8, v8
	v_fmac_f32_e32 v233, v9, v9
	v_fmac_f32_e32 v233, v10, v10
	v_fmac_f32_e32 v233, v11, v11
	s_waitcnt vmcnt(1)
	v_pk_fma_f32 v[4:5], v[4:5], v[162:163], v[202:203]
	v_pk_fma_f32 v[6:7], v[6:7], v[164:165], v[204:205]
	v_fmac_f32_e32 v233, v4, v4
	v_fmac_f32_e32 v233, v5, v5
	v_fmac_f32_e32 v233, v6, v6
	v_fmac_f32_e32 v233, v7, v7
	s_waitcnt vmcnt(0)
	v_pk_fma_f32 v[0:1], v[0:1], v[166:167], v[206:207]
	v_pk_fma_f32 v[2:3], v[2:3], v[168:169], v[208:209]
	v_fmac_f32_e32 v233, v0, v0
	v_fmac_f32_e32 v233, v1, v1
	v_fmac_f32_e32 v233, v2, v2
	v_fmac_f32_e32 v233, v3, v3
	s_cmpk_gt_u32 s42, 0xbf
	s_cbranch_scc1 .Lf2p16_nost
	global_store_dwordx4 v146, v[124:127], s[86:87]
	global_store_dwordx4 v146, v[120:123], s[86:87] offset:64
	global_store_dwordx4 v146, v[116:119], s[86:87] offset:512
	global_store_dwordx4 v146, v[112:115], s[86:87] offset:576
	s_add_u32 s86, s86, 0x10000
	s_addc_u32 s87, s87, 0
	global_store_dwordx4 v146, v[108:111], s[86:87]
	global_store_dwordx4 v146, v[104:107], s[86:87] offset:64
	global_store_dwordx4 v146, v[100:103], s[86:87] offset:512
	global_store_dwordx4 v146, v[96:99], s[86:87] offset:576
	s_add_u32 s86, s86, 0x10000
	s_addc_u32 s87, s87, 0
	global_store_dwordx4 v146, v[92:95], s[86:87]
	global_store_dwordx4 v146, v[88:91], s[86:87] offset:64
	global_store_dwordx4 v146, v[84:87], s[86:87] offset:512
	global_store_dwordx4 v146, v[80:83], s[86:87] offset:576
	s_add_u32 s86, s86, 0x10000
	s_addc_u32 s87, s87, 0
	global_store_dwordx4 v146, v[76:79], s[86:87]
	global_store_dwordx4 v146, v[72:75], s[86:87] offset:64
	global_store_dwordx4 v146, v[68:71], s[86:87] offset:512
	global_store_dwordx4 v146, v[64:67], s[86:87] offset:576
	s_add_u32 s86, s86, 0x50000
	s_addc_u32 s87, s87, 0
	global_store_dwordx4 v146, v[60:63], s[86:87]
	global_store_dwordx4 v146, v[56:59], s[86:87] offset:64
	global_store_dwordx4 v146, v[52:55], s[86:87] offset:512
	global_store_dwordx4 v146, v[48:51], s[86:87] offset:576
	s_add_u32 s86, s86, 0x10000
	s_addc_u32 s87, s87, 0
	global_store_dwordx4 v146, v[44:47], s[86:87]
	global_store_dwordx4 v146, v[40:43], s[86:87] offset:64
	global_store_dwordx4 v146, v[36:39], s[86:87] offset:512
	global_store_dwordx4 v146, v[32:35], s[86:87] offset:576
	s_add_u32 s86, s86, 0x10000
	s_addc_u32 s87, s87, 0
	global_store_dwordx4 v146, v[28:31], s[86:87]
	global_store_dwordx4 v146, v[24:27], s[86:87] offset:64
	global_store_dwordx4 v146, v[20:23], s[86:87] offset:512
	global_store_dwordx4 v146, v[16:19], s[86:87] offset:576
	s_add_u32 s86, s86, 0x10000
	s_addc_u32 s87, s87, 0
	global_store_dwordx4 v146, v[12:15], s[86:87]
	global_store_dwordx4 v146, v[8:11], s[86:87] offset:64
	global_store_dwordx4 v146, v[4:7], s[86:87] offset:512
	global_store_dwordx4 v146, v[0:3], s[86:87] offset:576
.Lf2p16_nost:
	v_mov_b64_e32 v[166:167], v[0:1]
	v_mov_b64_e32 v[168:169], v[2:3]
	s_mov_b32 s75, s28
	s_mov_b64 s[40:41], s[36:37]
	s_mov_b64 s[48:49], s[34:35]
	s_mov_b32 s10, s30
	s_and_b64 vcc, exec, s[8:9]
	s_cbranch_vccz .LBB0_2046
	s_waitcnt vmcnt(0)
	s_cmpk_gt_u32 s45, 0xff
	s_cbranch_scc1 .LBB0_2053
	s_barrier

.LBB0_2054:
	s_and_b64 vcc, exec, s[6:7]
	s_cbranch_vccnz .LBB0_2078
	s_lshr_b32 s3, s3, 29
	s_add_i32 s3, s2, s3
	s_ashr_i32 s6, s3, 3
	s_and_b32 s3, s3, -8
	s_sub_i32 s2, s2, s3
	s_lshr_b32 s3, s2, 31
	s_or_b32 s3, s3, 24
	s_mul_i32 s21, s3, s2
	s_add_i32 s21, s21, s6
	s_ashr_i32 s2, s21, 31
	s_lshr_b32 s2, s2, 27
	s_add_i32 s2, s21, s2
	s_ashr_i32 s22, s2, 5
	s_lshl_b32 s6, s22, 3
	s_sub_i32 s3, 48, s6
	s_min_u32 s7, s3, 8
	s_andn2_b32 s2, s2, 31
	s_sub_i32 s8, s21, s2
	v_cvt_f32_ubyte0_e32 v1, s7
	v_cvt_f32_i32_e32 v0, s8
	v_rcp_iflag_f32_e32 v2, v1
	s_ashr_i32 s2, s8, 30
	s_or_b32 s9, s2, 1
	v_mul_f32_e32 v2, v0, v2
	v_trunc_f32_e32 v2, v2
	v_fma_f32 v0, -v2, v1, v0
	v_cvt_i32_f32_e32 v2, v2
	v_cmp_ge_f32_e64 s[2:3], |v0|, v1
	s_and_b64 s[2:3], s[2:3], exec
	s_cselect_b32 s2, s9, 0
	v_readfirstlane_b32 s20, v2
	s_add_i32 s20, s20, s2
	s_mul_i32 s23, s20, s7
	s_sub_i32 s2, s8, s23
	s_sext_i32_i8 s2, s2
	s_add_i32 s2, s6, s2
	v_and_b32_e32 v178, 63, v170
	v_lshrrev_b32_e32 v179, 6, v170
	v_and_b32_e32 v180, 15, v178
	v_and_b32_e32 v181, 3, v179
	v_lshrrev_b32_e32 v179, 2, v179
	v_lshl_add_u32 v180, v179, 6, v180
	v_lshlrev_b32_e32 v180, 2, v180
	v_lshl_add_u32 v180, v181, 10, v180
	v_add_u32_e32 v180, 0x20000, v180
	ds_bpermute_b32 v182, v172, v226
	ds_bpermute_b32 v183, v172, v227
	ds_bpermute_b32 v184, v172, v228
	ds_bpermute_b32 v185, v172, v229
	ds_bpermute_b32 v186, v172, v230
	ds_bpermute_b32 v187, v172, v231
	ds_bpermute_b32 v188, v172, v232
	ds_bpermute_b32 v189, v172, v233
	s_waitcnt lgkmcnt(7)
	v_add_f32_e32 v226, v226, v182
	s_waitcnt lgkmcnt(6)
	v_add_f32_e32 v227, v227, v183
	s_waitcnt lgkmcnt(5)
	v_add_f32_e32 v228, v228, v184
	s_waitcnt lgkmcnt(4)
	v_add_f32_e32 v229, v229, v185
	s_waitcnt lgkmcnt(3)
	v_add_f32_e32 v230, v230, v186
	s_waitcnt lgkmcnt(2)
	v_add_f32_e32 v231, v231, v187
	s_waitcnt lgkmcnt(1)
	v_add_f32_e32 v232, v232, v188
	s_waitcnt lgkmcnt(0)
	v_add_f32_e32 v233, v233, v189
	ds_bpermute_b32 v182, v171, v226
	ds_bpermute_b32 v183, v171, v227
	ds_bpermute_b32 v184, v171, v228
	ds_bpermute_b32 v185, v171, v229
	ds_bpermute_b32 v186, v171, v230
	ds_bpermute_b32 v187, v171, v231
	ds_bpermute_b32 v188, v171, v232
	ds_bpermute_b32 v189, v171, v233
	s_waitcnt lgkmcnt(7)
	v_add_f32_e32 v226, v226, v182
	s_waitcnt lgkmcnt(6)
	v_add_f32_e32 v227, v227, v183
	s_waitcnt lgkmcnt(5)
	v_add_f32_e32 v228, v228, v184
	s_waitcnt lgkmcnt(4)
	v_add_f32_e32 v229, v229, v185
	s_waitcnt lgkmcnt(3)
	v_add_f32_e32 v230, v230, v186
	s_waitcnt lgkmcnt(2)
	v_add_f32_e32 v231, v231, v187
	s_waitcnt lgkmcnt(1)
	v_add_f32_e32 v232, v232, v188
	s_waitcnt lgkmcnt(0)
	v_add_f32_e32 v233, v233, v189
	ds_write_b32 v180, v226
	ds_write_b32 v180, v227 offset:64
	ds_write_b32 v180, v228 offset:128
	ds_write_b32 v180, v229 offset:192
	ds_write_b32 v180, v230 offset:512
	ds_write_b32 v180, v231 offset:576
	ds_write_b32 v180, v232 offset:640
	ds_write_b32 v180, v233 offset:704
	s_waitcnt lgkmcnt(0)
	s_barrier
	v_readfirstlane_b32 s60, v170
	s_and_b32 s62, s20, 3
	s_lshl_b32 s61, s2, 2
	s_add_i32 s61, s61, s62
	s_lshl_b32 s61, s61, 10
	s_add_u32 s62, s16, s61
	s_addc_u32 s63, s17, 0
	s_add_u32 s62, s62, 0xc0000
	s_addc_u32 s63, s63, 0
	s_cmp_lt_u32 s60, 256
	s_cbranch_scc0 .Lf2p16_nop
	v_lshlrev_b32_e32 v190, 2, v170
	v_add_u32_e32 v191, 0x20000, v190
	ds_read_b32 v192, v191
	ds_read_b32 v193, v191 offset:1024
	ds_read_b32 v194, v191 offset:2048
	ds_read_b32 v195, v191 offset:3072
	s_waitcnt lgkmcnt(0)
	v_add_f32_e32 v192, v192, v193
	v_add_f32_e32 v194, v194, v195
	v_add_f32_e32 v192, v192, v194
	global_store_dword v190, v192, s[62:63] sc1
.Lf2p16_nop:
	s_waitcnt vmcnt(0)
	s_barrier
	s_and_saveexec_b64 s[6:7], s[38:39]
	s_cbranch_execz .LBB0_2067
	s_ashr_i32 s3, s2, 31
	s_lshl_b64 s[8:9], s[2:3], 2
	s_mov_b64 s[10:11], exec
	s_add_u32 s3, s16, s8
	s_addc_u32 s9, s17, s9
	buffer_wbl2 sc1
	s_waitcnt vmcnt(0) lgkmcnt(0)
	s_waitcnt vmcnt(0)
	v_mbcnt_lo_u32_b32 v0, s10, 0
	s_add_u32 s8, s3, 0x779bb00
	v_mbcnt_hi_u32_b32 v0, s11, v0
	s_addc_u32 s9, s9, 0
	v_cmp_eq_u32_e32 vcc, 0, v0
	s_and_saveexec_b64 s[18:19], vcc
	s_cbranch_execz .LBB0_2058
	s_bcnt1_i32_b64 s3, s[10:11]
	v_mov_b32_e32 v0, 0
	v_mov_b32_e32 v1, s3
	global_atomic_add v0, v1, s[8:9]

.LBB0_2067:
	s_or_b64 exec, exec, s[6:7]
	s_sext_i32_i8 s3, s20
	s_lshl_b32 s2, s2, 8
	s_lshl_b32 s3, s3, 6
	s_add_i32 s20, s2, s3
	s_add_u32 s18, s16, 0x56bc000
	s_addc_u32 s19, s17, 0
	s_sub_i32 s6, s21, s23
	s_lshl_b32 s7, s22, 5
	s_sub_i32 s6, s6, s7
	s_sext_i32_i8 s6, s6
	s_lshl_b32 s6, s6, 8
	v_mov_b32_e32 v1, v170
	s_lshl_b32 s2, s22, 11
	s_add_i32 s3, s3, s6
	s_waitcnt lgkmcnt(0)
	s_barrier
	s_load_dwordx2 s[52:53], s[0:1], 0xe8
	s_load_dwordx4 s[68:71], s[0:1], 0xd8
	s_mov_b32 s66, s20
	v_readfirstlane_b32 s60, v170
	v_and_b32_e32 v194, 63, v170
	v_lshrrev_b32_e32 v195, 6, v170
	v_and_b32_e32 v196, 15, v194
	v_lshrrev_b32_e32 v194, 4, v194
	v_and_b32_e32 v197, 3, v195
	v_lshrrev_b32_e32 v195, 2, v195
	v_lshl_add_u32 v196, v195, 6, v196
	v_lshl_add_u32 v197, v197, 5, 0
	v_lshl_add_u32 v197, v194, 2, v197
	s_lshr_b32 s64, s66, 8
	s_lshr_b32 s65, s66, 6
	s_and_b32 s65, s65, 3
	s_lshl_b32 s67, s65, 8
	v_add_u32_e32 v197, s67, v197
	s_waitcnt lgkmcnt(0)
	s_lshl_b32 s61, s64, 12
	s_add_u32 s62, s52, s61
	s_addc_u32 s63, s53, 0
	s_add_u32 s62, s62, 0xc0000
	s_addc_u32 s63, s63, 0
	s_cmp_lt_u32 s60, 256
	s_cbranch_scc0 .Lf2p16_nor
	v_lshlrev_b32_e32 v190, 2, v170
	global_load_dword v192, v190, s[62:63] sc1
	global_load_dword v193, v190, s[62:63] offset:1024 sc1
	global_load_dword v198, v190, s[62:63] offset:2048 sc1
	global_load_dword v199, v190, s[62:63] offset:3072 sc1
	v_mov_b32_e32 v191, 0x358637bd
	s_waitcnt vmcnt(0)
	v_add_f32_e32 v192, v192, v193
	v_add_f32_e32 v198, v198, v199
	v_add_f32_e32 v192, v192, v198
	v_fmamk_f32 v192, v192, 0x3a800000, v191
	v_rsq_f32_e32 v192, v192
	v_add_u32_e32 v191, 0x21000, v190
	s_nop 0
	ds_write_b32 v191, v192
.Lf2p16_nor:
	s_waitcnt lgkmcnt(0)
	s_barrier
	v_lshlrev_b32_e32 v198, 2, v197
	global_load_dwordx4 v[200:203], v198, s[68:69]
	global_load_dwordx4 v[204:207], v198, s[68:69] offset:64
	global_load_dwordx4 v[208:211], v198, s[68:69] offset:512
	global_load_dwordx4 v[212:215], v198, s[68:69] offset:576
	v_lshlrev_b32_e32 v199, 2, v196
	v_add_u32_e32 v199, 0x21000, v199
	ds_read_b32 v178, v199
	ds_read_b32 v180, v199 offset:64
	ds_read_b32 v182, v199 offset:128
	ds_read_b32 v184, v199 offset:192
	ds_read_b32 v186, v199 offset:512
	ds_read_b32 v188, v199 offset:576
	ds_read_b32 v190, v199 offset:640
	ds_read_b32 v192, v199 offset:704
	s_lshl_b32 s67, s64, 8
	v_add_u32_e32 v196, s67, v196
	v_lshlrev_b32_e32 v232, 12, v196
	v_lshl_add_u32 v232, v197, 2, v232
	s_mov_b64 s[56:57], s[70:71]
	s_waitcnt vmcnt(0) lgkmcnt(0)
	v_pk_mul_f32 v[124:125], v[124:125], v[178:179] op_sel_hi:[1,0]
	v_pk_mul_f32 v[126:127], v[126:127], v[178:179] op_sel_hi:[1,0]
	v_pk_mul_f32 v[124:125], v[124:125], v[200:201]
	v_pk_mul_f32 v[126:127], v[126:127], v[202:203]
	global_store_dwordx4 v232, v[124:127], s[56:57] nt
	v_pk_mul_f32 v[120:121], v[120:121], v[178:179] op_sel_hi:[1,0]
	v_pk_mul_f32 v[122:123], v[122:123], v[178:179] op_sel_hi:[1,0]
	v_pk_mul_f32 v[120:121], v[120:121], v[204:205]
	v_pk_mul_f32 v[122:123], v[122:123], v[206:207]
	global_store_dwordx4 v232, v[120:123], s[56:57] offset:64 nt
	v_pk_mul_f32 v[116:117], v[116:117], v[178:179] op_sel_hi:[1,0]
	v_pk_mul_f32 v[118:119], v[118:119], v[178:179] op_sel_hi:[1,0]
	v_pk_mul_f32 v[116:117], v[116:117], v[208:209]
	v_pk_mul_f32 v[118:119], v[118:119], v[210:211]
	global_store_dwordx4 v232, v[116:119], s[56:57] offset:512 nt
	v_pk_mul_f32 v[112:113], v[112:113], v[178:179] op_sel_hi:[1,0]
	v_pk_mul_f32 v[114:115], v[114:115], v[178:179] op_sel_hi:[1,0]
	v_pk_mul_f32 v[112:113], v[112:113], v[212:213]
	v_pk_mul_f32 v[114:115], v[114:115], v[214:215]
	global_store_dwordx4 v232, v[112:115], s[56:57] offset:576 nt
	s_add_u32 s56, s56, 0x10000
	s_addc_u32 s57, s57, 0
	v_pk_mul_f32 v[108:109], v[108:109], v[180:181] op_sel_hi:[1,0]
	v_pk_mul_f32 v[110:111], v[110:111], v[180:181] op_sel_hi:[1,0]
	v_pk_mul_f32 v[108:109], v[108:109], v[200:201]
	v_pk_mul_f32 v[110:111], v[110:111], v[202:203]
	global_store_dwordx4 v232, v[108:111], s[56:57] nt
	v_pk_mul_f32 v[104:105], v[104:105], v[180:181] op_sel_hi:[1,0]
	v_pk_mul_f32 v[106:107], v[106:107], v[180:181] op_sel_hi:[1,0]
	v_pk_mul_f32 v[104:105], v[104:105], v[204:205]
	v_pk_mul_f32 v[106:107], v[106:107], v[206:207]
	global_store_dwordx4 v232, v[104:107], s[56:57] offset:64 nt
	v_pk_mul_f32 v[100:101], v[100:101], v[180:181] op_sel_hi:[1,0]
	v_pk_mul_f32 v[102:103], v[102:103], v[180:181] op_sel_hi:[1,0]
	v_pk_mul_f32 v[100:101], v[100:101], v[208:209]
	v_pk_mul_f32 v[102:103], v[102:103], v[210:211]
	global_store_dwordx4 v232, v[100:103], s[56:57] offset:512 nt
	v_pk_mul_f32 v[96:97], v[96:97], v[180:181] op_sel_hi:[1,0]
	v_pk_mul_f32 v[98:99], v[98:99], v[180:181] op_sel_hi:[1,0]
	v_pk_mul_f32 v[96:97], v[96:97], v[212:213]
	v_pk_mul_f32 v[98:99], v[98:99], v[214:215]
	global_store_dwordx4 v232, v[96:99], s[56:57] offset:576 nt
	s_add_u32 s56, s56, 0x10000
	s_addc_u32 s57, s57, 0
	v_pk_mul_f32 v[92:93], v[92:93], v[182:183] op_sel_hi:[1,0]
	v_pk_mul_f32 v[94:95], v[94:95], v[182:183] op_sel_hi:[1,0]
	v_pk_mul_f32 v[92:93], v[92:93], v[200:201]
	v_pk_mul_f32 v[94:95], v[94:95], v[202:203]
	global_store_dwordx4 v232, v[92:95], s[56:57] nt
	v_pk_mul_f32 v[88:89], v[88:89], v[182:183] op_sel_hi:[1,0]
	v_pk_mul_f32 v[90:91], v[90:91], v[182:183] op_sel_hi:[1,0]
	v_pk_mul_f32 v[88:89], v[88:89], v[204:205]
	v_pk_mul_f32 v[90:91], v[90:91], v[206:207]
	global_store_dwordx4 v232, v[88:91], s[56:57] offset:64 nt
	v_pk_mul_f32 v[84:85], v[84:85], v[182:183] op_sel_hi:[1,0]
	v_pk_mul_f32 v[86:87], v[86:87], v[182:183] op_sel_hi:[1,0]
	v_pk_mul_f32 v[84:85], v[84:85], v[208:209]
	v_pk_mul_f32 v[86:87], v[86:87], v[210:211]
	global_store_dwordx4 v232, v[84:87], s[56:57] offset:512 nt
	v_pk_mul_f32 v[80:81], v[80:81], v[182:183] op_sel_hi:[1,0]
	v_pk_mul_f32 v[82:83], v[82:83], v[182:183] op_sel_hi:[1,0]
	v_pk_mul_f32 v[80:81], v[80:81], v[212:213]
	v_pk_mul_f32 v[82:83], v[82:83], v[214:215]
	global_store_dwordx4 v232, v[80:83], s[56:57] offset:576 nt
	s_add_u32 s56, s56, 0x10000
	s_addc_u32 s57, s57, 0
	v_pk_mul_f32 v[76:77], v[76:77], v[184:185] op_sel_hi:[1,0]
	v_pk_mul_f32 v[78:79], v[78:79], v[184:185] op_sel_hi:[1,0]
	v_pk_mul_f32 v[76:77], v[76:77], v[200:201]
	v_pk_mul_f32 v[78:79], v[78:79], v[202:203]
	global_store_dwordx4 v232, v[76:79], s[56:57] nt
	v_pk_mul_f32 v[72:73], v[72:73], v[184:185] op_sel_hi:[1,0]
	v_pk_mul_f32 v[74:75], v[74:75], v[184:185] op_sel_hi:[1,0]
	v_pk_mul_f32 v[72:73], v[72:73], v[204:205]
	v_pk_mul_f32 v[74:75], v[74:75], v[206:207]
	global_store_dwordx4 v232, v[72:75], s[56:57] offset:64 nt
	v_pk_mul_f32 v[68:69], v[68:69], v[184:185] op_sel_hi:[1,0]
	v_pk_mul_f32 v[70:71], v[70:71], v[184:185] op_sel_hi:[1,0]
	v_pk_mul_f32 v[68:69], v[68:69], v[208:209]
	v_pk_mul_f32 v[70:71], v[70:71], v[210:211]
	global_store_dwordx4 v232, v[68:71], s[56:57] offset:512 nt
	v_pk_mul_f32 v[64:65], v[64:65], v[184:185] op_sel_hi:[1,0]
	v_pk_mul_f32 v[66:67], v[66:67], v[184:185] op_sel_hi:[1,0]
	v_pk_mul_f32 v[64:65], v[64:65], v[212:213]
	v_pk_mul_f32 v[66:67], v[66:67], v[214:215]
	global_store_dwordx4 v232, v[64:67], s[56:57] offset:576 nt
	s_add_u32 s56, s56, 0x50000
	s_addc_u32 s57, s57, 0
	v_pk_mul_f32 v[60:61], v[60:61], v[186:187] op_sel_hi:[1,0]
	v_pk_mul_f32 v[62:63], v[62:63], v[186:187] op_sel_hi:[1,0]
	v_pk_mul_f32 v[60:61], v[60:61], v[200:201]
	v_pk_mul_f32 v[62:63], v[62:63], v[202:203]
	global_store_dwordx4 v232, v[60:63], s[56:57] nt
	v_pk_mul_f32 v[56:57], v[56:57], v[186:187] op_sel_hi:[1,0]
	v_pk_mul_f32 v[58:59], v[58:59], v[186:187] op_sel_hi:[1,0]
	v_pk_mul_f32 v[56:57], v[56:57], v[204:205]
	v_pk_mul_f32 v[58:59], v[58:59], v[206:207]
	global_store_dwordx4 v232, v[56:59], s[56:57] offset:64 nt
	v_pk_mul_f32 v[52:53], v[52:53], v[186:187] op_sel_hi:[1,0]
	v_pk_mul_f32 v[54:55], v[54:55], v[186:187] op_sel_hi:[1,0]
	v_pk_mul_f32 v[52:53], v[52:53], v[208:209]
	v_pk_mul_f32 v[54:55], v[54:55], v[210:211]
	global_store_dwordx4 v232, v[52:55], s[56:57] offset:512 nt
	v_pk_mul_f32 v[48:49], v[48:49], v[186:187] op_sel_hi:[1,0]
	v_pk_mul_f32 v[50:51], v[50:51], v[186:187] op_sel_hi:[1,0]
	v_pk_mul_f32 v[48:49], v[48:49], v[212:213]
	v_pk_mul_f32 v[50:51], v[50:51], v[214:215]
	global_store_dwordx4 v232, v[48:51], s[56:57] offset:576 nt
	s_add_u32 s56, s56, 0x10000
	s_addc_u32 s57, s57, 0
	v_pk_mul_f32 v[44:45], v[44:45], v[188:189] op_sel_hi:[1,0]
	v_pk_mul_f32 v[46:47], v[46:47], v[188:189] op_sel_hi:[1,0]
	v_pk_mul_f32 v[44:45], v[44:45], v[200:201]
	v_pk_mul_f32 v[46:47], v[46:47], v[202:203]
	global_store_dwordx4 v232, v[44:47], s[56:57] nt
	v_pk_mul_f32 v[40:41], v[40:41], v[188:189] op_sel_hi:[1,0]
	v_pk_mul_f32 v[42:43], v[42:43], v[188:189] op_sel_hi:[1,0]
	v_pk_mul_f32 v[40:41], v[40:41], v[204:205]
	v_pk_mul_f32 v[42:43], v[42:43], v[206:207]
	global_store_dwordx4 v232, v[40:43], s[56:57] offset:64 nt
	v_pk_mul_f32 v[36:37], v[36:37], v[188:189] op_sel_hi:[1,0]
	v_pk_mul_f32 v[38:39], v[38:39], v[188:189] op_sel_hi:[1,0]
	v_pk_mul_f32 v[36:37], v[36:37], v[208:209]
	v_pk_mul_f32 v[38:39], v[38:39], v[210:211]
	global_store_dwordx4 v232, v[36:39], s[56:57] offset:512 nt
	v_pk_mul_f32 v[32:33], v[32:33], v[188:189] op_sel_hi:[1,0]
	v_pk_mul_f32 v[34:35], v[34:35], v[188:189] op_sel_hi:[1,0]
	v_pk_mul_f32 v[32:33], v[32:33], v[212:213]
	v_pk_mul_f32 v[34:35], v[34:35], v[214:215]
	global_store_dwordx4 v232, v[32:35], s[56:57] offset:576 nt
	s_add_u32 s56, s56, 0x10000
	s_addc_u32 s57, s57, 0
	v_pk_mul_f32 v[28:29], v[28:29], v[190:191] op_sel_hi:[1,0]
	v_pk_mul_f32 v[30:31], v[30:31], v[190:191] op_sel_hi:[1,0]
	v_pk_mul_f32 v[28:29], v[28:29], v[200:201]
	v_pk_mul_f32 v[30:31], v[30:31], v[202:203]
	global_store_dwordx4 v232, v[28:31], s[56:57] nt
	v_pk_mul_f32 v[24:25], v[24:25], v[190:191] op_sel_hi:[1,0]
	v_pk_mul_f32 v[26:27], v[26:27], v[190:191] op_sel_hi:[1,0]
	v_pk_mul_f32 v[24:25], v[24:25], v[204:205]
	v_pk_mul_f32 v[26:27], v[26:27], v[206:207]
	global_store_dwordx4 v232, v[24:27], s[56:57] offset:64 nt
	v_pk_mul_f32 v[20:21], v[20:21], v[190:191] op_sel_hi:[1,0]
	v_pk_mul_f32 v[22:23], v[22:23], v[190:191] op_sel_hi:[1,0]
	v_pk_mul_f32 v[20:21], v[20:21], v[208:209]
	v_pk_mul_f32 v[22:23], v[22:23], v[210:211]
	global_store_dwordx4 v232, v[20:23], s[56:57] offset:512 nt
	v_pk_mul_f32 v[16:17], v[16:17], v[190:191] op_sel_hi:[1,0]
	v_pk_mul_f32 v[18:19], v[18:19], v[190:191] op_sel_hi:[1,0]
	v_pk_mul_f32 v[16:17], v[16:17], v[212:213]
	v_pk_mul_f32 v[18:19], v[18:19], v[214:215]
	global_store_dwordx4 v232, v[16:19], s[56:57] offset:576 nt
	s_add_u32 s56, s56, 0x10000
	s_addc_u32 s57, s57, 0
	v_pk_mul_f32 v[12:13], v[12:13], v[192:193] op_sel_hi:[1,0]
	v_pk_mul_f32 v[14:15], v[14:15], v[192:193] op_sel_hi:[1,0]
	v_pk_mul_f32 v[12:13], v[12:13], v[200:201]
	v_pk_mul_f32 v[14:15], v[14:15], v[202:203]
	global_store_dwordx4 v232, v[12:15], s[56:57] nt
	v_pk_mul_f32 v[8:9], v[8:9], v[192:193] op_sel_hi:[1,0]
	v_pk_mul_f32 v[10:11], v[10:11], v[192:193] op_sel_hi:[1,0]
	v_pk_mul_f32 v[8:9], v[8:9], v[204:205]
	v_pk_mul_f32 v[10:11], v[10:11], v[206:207]
	global_store_dwordx4 v232, v[8:11], s[56:57] offset:64 nt
	v_pk_mul_f32 v[4:5], v[4:5], v[192:193] op_sel_hi:[1,0]
	v_pk_mul_f32 v[6:7], v[6:7], v[192:193] op_sel_hi:[1,0]
	v_pk_mul_f32 v[4:5], v[4:5], v[208:209]
	v_pk_mul_f32 v[6:7], v[6:7], v[210:211]
	global_store_dwordx4 v232, v[4:7], s[56:57] offset:512 nt
	v_pk_mul_f32 v[166:167], v[166:167], v[192:193] op_sel_hi:[1,0]
	v_pk_mul_f32 v[168:169], v[168:169], v[192:193] op_sel_hi:[1,0]
	v_pk_mul_f32 v[166:167], v[166:167], v[212:213]
	v_pk_mul_f32 v[168:169], v[168:169], v[214:215]
	global_store_dwordx4 v232, v[166:169], s[56:57] offset:576 nt
